# odd attention: K/V tile loads use 32-bit per-thread offsets with scalar tile bases
# speedup vs baseline: 1.0061x; 1.0061x over previous
.LBB0_429:
	s_mul_hi_u32 s31, s29, s18
	s_mul_i32 s30, s29, s18
	s_lshl_b64 s[28:29], s[30:31], 7
	s_add_u32 s22, s22, s28
	s_addc_u32 s23, s23, s29
	s_add_u32 s20, s20, s28
	s_addc_u32 s21, s21, s29
	v_mul_lo_u32 v190, v124, s18
	v_mul_lo_u32 v191, v126, s18
	v_mul_lo_u32 v192, v128, s18
	v_mul_lo_u32 v193, v130, s18
	v_lshl_add_u32 v190, v190, 1, v138
	v_lshl_add_u32 v191, v191, 1, v136
	v_lshl_add_u32 v192, v192, 1, v134
	v_lshl_add_u32 v193, v193, 1, v132
	global_load_dwordx4 v[24:27], v190, s[22:23]
	global_load_dwordx4 v[28:31], v191, s[22:23]
	global_load_dwordx4 v[40:43], v192, s[22:23]
	global_load_dwordx4 v[44:47], v193, s[22:23]
	global_load_dwordx4 v[32:35], v190, s[20:21]
	global_load_dwordx4 v[36:39], v191, s[20:21]
	global_load_dwordx4 v[16:19], v192, s[20:21]
	global_load_dwordx4 v[20:23], v193, s[20:21]
	s_mov_b32 s30, 0xf149f2ca
